# v38 + MLA loop v6: per-key-half exp-sum overflow checks; second-half exps and sums interleaved under the first half's P.V MFMAs (first half under QK2), no row-max tree in the main path
# speedup vs baseline: 1.0142x; 1.0017x over previous
.Lm_pd:
	v_cmp_lt_f32_e32 vcc, 0x47800000, v234
	s_cbranch_vccnz .Lm_RA
	v_add_f32_e32 v193, v193, v234
	v_cvt_pk_bf16_f32 v226, v100, v101
	v_cvt_pk_bf16_f32 v227, v102, v103
	v_cvt_pk_bf16_f32 v228, v104, v105
	v_cvt_pk_bf16_f32 v229, v106, v107
	v_cvt_pk_bf16_f32 v230, v108, v109
	v_cvt_pk_bf16_f32 v231, v110, v111
	v_cvt_pk_bf16_f32 v232, v112, v113
	v_cvt_pk_bf16_f32 v233, v114, v115
	ds_read_b64_tr_b16 v[100:101], v197 offset:30720
	ds_read_b64_tr_b16 v[102:103], v197 offset:33280
	ds_read_b64_tr_b16 v[104:105], v197 offset:30784
	ds_read_b64_tr_b16 v[106:107], v197 offset:33344
	ds_read_b64_tr_b16 v[108:109], v197 offset:30848
	ds_read_b64_tr_b16 v[110:111], v197 offset:33408
	ds_read_b64_tr_b16 v[112:113], v197 offset:30912
	ds_read_b64_tr_b16 v[114:115], v197 offset:33472
	s_waitcnt lgkmcnt(14)
	v_mfma_f32_32x32x16_bf16 v[68:83], v[10:13], v[226:229], v[68:83]
	v_exp_f32_e32 v84, v84
	v_exp_f32_e32 v85, v85
	v_exp_f32_e32 v86, v86
	v_exp_f32_e32 v87, v87
	s_waitcnt lgkmcnt(12)
	v_mfma_f32_32x32x16_bf16 v[52:67], v[14:17], v[226:229], v[52:67]
	v_exp_f32_e32 v88, v88
	v_exp_f32_e32 v89, v89
	v_exp_f32_e32 v90, v90
	v_exp_f32_e32 v91, v91
	s_waitcnt lgkmcnt(10)
	v_mfma_f32_32x32x16_bf16 v[36:51], v[202:205], v[226:229], v[36:51]
	v_exp_f32_e32 v92, v92
	v_exp_f32_e32 v93, v93
	v_exp_f32_e32 v94, v94
	v_exp_f32_e32 v95, v95
	s_waitcnt lgkmcnt(8)
	v_mfma_f32_32x32x16_bf16 v[20:35], v[206:209], v[226:229], v[20:35]
	v_exp_f32_e32 v96, v96
	v_exp_f32_e32 v97, v97
	v_exp_f32_e32 v98, v98
	v_exp_f32_e32 v99, v99
	ds_read_b64_tr_b16 v[10:11], v197 offset:35840
	ds_read_b64_tr_b16 v[12:13], v197 offset:38400
	ds_read_b64_tr_b16 v[14:15], v197 offset:35904
	ds_read_b64_tr_b16 v[16:17], v197 offset:38464
	ds_read_b64_tr_b16 v[202:203], v197 offset:35968
	ds_read_b64_tr_b16 v[204:205], v197 offset:38528
	ds_read_b64_tr_b16 v[206:207], v197 offset:36032
	ds_read_b64_tr_b16 v[208:209], v197 offset:38592
	s_waitcnt lgkmcnt(14)
	v_mfma_f32_32x32x16_bf16 v[68:83], v[100:103], v[230:233], v[68:83]
	v_add_f32_e32 v240, 0, v84
	v_add_f32_e32 v240, v85, v240
	v_add_f32_e32 v240, v86, v240
	v_add_f32_e32 v240, v87, v240
	s_waitcnt lgkmcnt(12)
	v_mfma_f32_32x32x16_bf16 v[52:67], v[104:107], v[230:233], v[52:67]
	v_add_f32_e32 v240, v88, v240
	v_add_f32_e32 v240, v89, v240
	v_add_f32_e32 v240, v90, v240
	v_add_f32_e32 v240, v91, v240
	s_waitcnt lgkmcnt(10)
	v_mfma_f32_32x32x16_bf16 v[36:51], v[108:111], v[230:233], v[36:51]
	v_add_f32_e32 v240, v92, v240
	v_add_f32_e32 v240, v93, v240
	v_add_f32_e32 v240, v94, v240
	v_add_f32_e32 v240, v95, v240
	s_waitcnt lgkmcnt(8)
	v_mfma_f32_32x32x16_bf16 v[20:35], v[112:115], v[230:233], v[20:35]
	v_add_f32_e32 v240, v96, v240
	v_add_f32_e32 v240, v97, v240
	v_add_f32_e32 v240, v98, v240
	v_add_f32_e32 v240, v99, v240
	ds_read_b64_tr_b16 v[100:101], v197 offset:40960
	ds_read_b64_tr_b16 v[102:103], v197 offset:43520
	ds_read_b64_tr_b16 v[104:105], v197 offset:41024
	ds_read_b64_tr_b16 v[106:107], v197 offset:43584
	ds_read_b64_tr_b16 v[108:109], v197 offset:41088
	ds_read_b64_tr_b16 v[110:111], v197 offset:43648
	ds_read_b64_tr_b16 v[112:113], v197 offset:41152
	ds_read_b64_tr_b16 v[114:115], v197 offset:43712
	v_cmp_lt_f32_e32 vcc, 0x47800000, v240
	s_cbranch_vccnz .Lm_RB
.Lm_postB:
	v_add_f32_e32 v193, v193, v240
	v_cvt_pk_bf16_f32 v226, v84, v85
	v_cvt_pk_bf16_f32 v227, v86, v87
	v_cvt_pk_bf16_f32 v228, v88, v89
	v_cvt_pk_bf16_f32 v229, v90, v91
	v_cvt_pk_bf16_f32 v230, v92, v93
	v_cvt_pk_bf16_f32 v231, v94, v95
	v_cvt_pk_bf16_f32 v232, v96, v97
	v_cvt_pk_bf16_f32 v233, v98, v99
	s_waitcnt lgkmcnt(14)
	v_mfma_f32_32x32x16_bf16 v[68:83], v[10:13], v[226:229], v[68:83]
	s_waitcnt lgkmcnt(12)
	v_mfma_f32_32x32x16_bf16 v[52:67], v[14:17], v[226:229], v[52:67]
	s_waitcnt lgkmcnt(10)
	v_mfma_f32_32x32x16_bf16 v[36:51], v[202:205], v[226:229], v[36:51]
	s_waitcnt lgkmcnt(8)
	v_mfma_f32_32x32x16_bf16 v[20:35], v[206:209], v[226:229], v[20:35]
	s_waitcnt lgkmcnt(6)
	v_mfma_f32_32x32x16_bf16 v[68:83], v[100:103], v[230:233], v[68:83]
	s_waitcnt lgkmcnt(4)
	v_mfma_f32_32x32x16_bf16 v[52:67], v[104:107], v[230:233], v[52:67]
	s_waitcnt lgkmcnt(2)
	v_mfma_f32_32x32x16_bf16 v[36:51], v[108:111], v[230:233], v[36:51]
	s_waitcnt lgkmcnt(0)
	v_mfma_f32_32x32x16_bf16 v[20:35], v[112:115], v[230:233], v[20:35]

.Lm_RA:
	s_waitcnt lgkmcnt(0)
	ds_read_b128 v[10:13], v8
	ds_read_b128 v[14:17], v8 offset:32
	ds_read_b128 v[202:205], v8 offset:64
	ds_read_b128 v[206:209], v8 offset:96
	s_waitcnt lgkmcnt(3)
	v_mfma_f32_32x32x16_bf16 v[100:115], v[10:13], v[116:119], v[210:225]
	ds_read_b128 v[10:13], v8 offset:128
	s_waitcnt lgkmcnt(3)
	v_mfma_f32_32x32x16_bf16 v[100:115], v[14:17], v[120:123], v[100:115]
	ds_read_b128 v[14:17], v8 offset:160
	s_waitcnt lgkmcnt(3)
	v_mfma_f32_32x32x16_bf16 v[100:115], v[202:205], v[124:127], v[100:115]
	ds_read_b128 v[202:205], v8 offset:192
	s_waitcnt lgkmcnt(3)
	v_mfma_f32_32x32x16_bf16 v[100:115], v[206:209], v[132:135], v[100:115]
	ds_read_b128 v[206:209], v8 offset:224
	s_waitcnt lgkmcnt(3)
	v_mfma_f32_32x32x16_bf16 v[100:115], v[10:13], v[136:139], v[100:115]
	ds_read_b128 v[10:13], v8 offset:256
	s_waitcnt lgkmcnt(3)
	v_mfma_f32_32x32x16_bf16 v[100:115], v[14:17], v[140:143], v[100:115]
	ds_read_b128 v[14:17], v8 offset:288
	s_waitcnt lgkmcnt(3)
	v_mfma_f32_32x32x16_bf16 v[100:115], v[202:205], v[144:147], v[100:115]
	ds_read_b128 v[202:205], v8 offset:320
	s_waitcnt lgkmcnt(3)
	v_mfma_f32_32x32x16_bf16 v[100:115], v[206:209], v[148:151], v[100:115]
	ds_read_b128 v[206:209], v8 offset:352
	s_waitcnt lgkmcnt(3)
	v_mfma_f32_32x32x16_bf16 v[100:115], v[10:13], v[152:155], v[100:115]
	ds_read_b128 v[10:13], v8 offset:12800
	s_waitcnt lgkmcnt(3)
	v_mfma_f32_32x32x16_bf16 v[100:115], v[14:17], v[156:159], v[100:115]
	ds_read_b128 v[14:17], v8 offset:12832
	s_waitcnt lgkmcnt(3)
	v_mfma_f32_32x32x16_bf16 v[100:115], v[202:205], v[160:163], v[100:115]
	ds_read_b128 v[202:205], v8 offset:12864
	s_waitcnt lgkmcnt(3)
	v_mfma_f32_32x32x16_bf16 v[100:115], v[206:209], v[164:167], v[100:115]
	ds_read_b128 v[206:209], v8 offset:12896
	s_waitcnt lgkmcnt(3)
	v_mfma_f32_32x32x16_bf16 v[84:99], v[10:13], v[116:119], v[210:225]
	ds_read_b128 v[10:13], v8 offset:12928
	s_waitcnt lgkmcnt(3)
	v_mfma_f32_32x32x16_bf16 v[84:99], v[14:17], v[120:123], v[84:99]
	ds_read_b128 v[14:17], v8 offset:12960
	s_waitcnt lgkmcnt(3)
	v_mfma_f32_32x32x16_bf16 v[84:99], v[202:205], v[124:127], v[84:99]
	ds_read_b128 v[202:205], v8 offset:12992
	s_waitcnt lgkmcnt(3)
	v_mfma_f32_32x32x16_bf16 v[84:99], v[206:209], v[132:135], v[84:99]
	ds_read_b128 v[206:209], v8 offset:13024
	s_waitcnt lgkmcnt(3)
	v_mfma_f32_32x32x16_bf16 v[84:99], v[10:13], v[136:139], v[84:99]
	ds_read_b128 v[10:13], v8 offset:13056
	s_waitcnt lgkmcnt(3)
	v_mfma_f32_32x32x16_bf16 v[84:99], v[14:17], v[140:143], v[84:99]
	ds_read_b128 v[14:17], v8 offset:13088
	s_waitcnt lgkmcnt(3)
	v_mfma_f32_32x32x16_bf16 v[84:99], v[202:205], v[144:147], v[84:99]
	ds_read_b128 v[202:205], v8 offset:13120
	s_waitcnt lgkmcnt(3)
	v_mfma_f32_32x32x16_bf16 v[84:99], v[206:209], v[148:151], v[84:99]
	ds_read_b128 v[206:209], v8 offset:13152
	s_waitcnt lgkmcnt(3)
	v_mfma_f32_32x32x16_bf16 v[84:99], v[10:13], v[152:155], v[84:99]
	s_waitcnt lgkmcnt(2)
	v_mfma_f32_32x32x16_bf16 v[84:99], v[14:17], v[156:159], v[84:99]
	s_waitcnt lgkmcnt(1)
	v_mfma_f32_32x32x16_bf16 v[84:99], v[202:205], v[160:163], v[84:99]
	s_waitcnt lgkmcnt(0)
	v_mfma_f32_32x32x16_bf16 v[84:99], v[206:209], v[164:167], v[84:99]
	v_max3_f32 v235, v100, v101, v102
	v_max3_f32 v235, v235, v103, v104
	v_max3_f32 v235, v235, v105, v106
	v_max3_f32 v235, v235, v107, v108
	v_max3_f32 v235, v235, v109, v110
	v_max3_f32 v235, v235, v111, v112
	v_max3_f32 v235, v235, v113, v114
	s_nop 4
	v_max3_f32 v235, v235, v115, v84
	v_max3_f32 v235, v235, v85, v86
	v_max3_f32 v235, v235, v87, v88
	v_max3_f32 v235, v235, v89, v90
	v_max3_f32 v235, v235, v91, v92
	v_max3_f32 v235, v235, v93, v94
	v_max3_f32 v235, v235, v95, v96
	v_max3_f32 v235, v235, v97, v98
	v_max3_f32 v235, v235, v99, v99
	v_mov_b32_e32 v237, v235
	v_mov_b32_e32 v239, v235
	s_nop 1
	v_permlane32_swap_b32_e32 v237, v239
	v_cndmask_b32_e64 v237, v237, v239, s[4:5]
	v_max_f32_e32 v237, v237, v237
	v_max_f32_e32 v236, v235, v237
	v_max_f32_e32 v236, 0, v236
	v_exp_f32_e64 v238, -v236
	v_pk_add_f32 v[100:101], v[100:101], v[236:237] op_sel_hi:[1,0] neg_lo:[0,1] neg_hi:[0,1]
	v_pk_add_f32 v[102:103], v[102:103], v[236:237] op_sel_hi:[1,0] neg_lo:[0,1] neg_hi:[0,1]
	v_pk_add_f32 v[104:105], v[104:105], v[236:237] op_sel_hi:[1,0] neg_lo:[0,1] neg_hi:[0,1]
	v_pk_add_f32 v[106:107], v[106:107], v[236:237] op_sel_hi:[1,0] neg_lo:[0,1] neg_hi:[0,1]
	v_pk_add_f32 v[108:109], v[108:109], v[236:237] op_sel_hi:[1,0] neg_lo:[0,1] neg_hi:[0,1]
	v_pk_add_f32 v[110:111], v[110:111], v[236:237] op_sel_hi:[1,0] neg_lo:[0,1] neg_hi:[0,1]
	v_pk_add_f32 v[112:113], v[112:113], v[236:237] op_sel_hi:[1,0] neg_lo:[0,1] neg_hi:[0,1]
	v_pk_add_f32 v[114:115], v[114:115], v[236:237] op_sel_hi:[1,0] neg_lo:[0,1] neg_hi:[0,1]
	v_pk_add_f32 v[84:85], v[84:85], v[236:237] op_sel_hi:[1,0] neg_lo:[0,1] neg_hi:[0,1]
	v_pk_add_f32 v[86:87], v[86:87], v[236:237] op_sel_hi:[1,0] neg_lo:[0,1] neg_hi:[0,1]
	v_pk_add_f32 v[88:89], v[88:89], v[236:237] op_sel_hi:[1,0] neg_lo:[0,1] neg_hi:[0,1]
	v_pk_add_f32 v[90:91], v[90:91], v[236:237] op_sel_hi:[1,0] neg_lo:[0,1] neg_hi:[0,1]
	v_pk_add_f32 v[92:93], v[92:93], v[236:237] op_sel_hi:[1,0] neg_lo:[0,1] neg_hi:[0,1]
	v_pk_add_f32 v[94:95], v[94:95], v[236:237] op_sel_hi:[1,0] neg_lo:[0,1] neg_hi:[0,1]
	v_pk_add_f32 v[96:97], v[96:97], v[236:237] op_sel_hi:[1,0] neg_lo:[0,1] neg_hi:[0,1]
	v_pk_add_f32 v[98:99], v[98:99], v[236:237] op_sel_hi:[1,0] neg_lo:[0,1] neg_hi:[0,1]
	v_pk_add_f32 v[210:211], v[210:211], v[236:237] op_sel_hi:[1,0] neg_lo:[0,1] neg_hi:[0,1]
	v_pk_add_f32 v[212:213], v[212:213], v[236:237] op_sel_hi:[1,0] neg_lo:[0,1] neg_hi:[0,1]
	v_pk_add_f32 v[214:215], v[214:215], v[236:237] op_sel_hi:[1,0] neg_lo:[0,1] neg_hi:[0,1]
	v_pk_add_f32 v[216:217], v[216:217], v[236:237] op_sel_hi:[1,0] neg_lo:[0,1] neg_hi:[0,1]
	v_pk_add_f32 v[218:219], v[218:219], v[236:237] op_sel_hi:[1,0] neg_lo:[0,1] neg_hi:[0,1]
	v_pk_add_f32 v[220:221], v[220:221], v[236:237] op_sel_hi:[1,0] neg_lo:[0,1] neg_hi:[0,1]
	v_pk_add_f32 v[222:223], v[222:223], v[236:237] op_sel_hi:[1,0] neg_lo:[0,1] neg_hi:[0,1]
	v_pk_add_f32 v[224:225], v[224:225], v[236:237] op_sel_hi:[1,0] neg_lo:[0,1] neg_hi:[0,1]
	v_mul_f32_e32 v193, v193, v238
	v_pk_mul_f32 v[68:69], v[68:69], v[238:239] op_sel_hi:[1,0]
	v_pk_mul_f32 v[70:71], v[70:71], v[238:239] op_sel_hi:[1,0]
	v_pk_mul_f32 v[72:73], v[72:73], v[238:239] op_sel_hi:[1,0]
	v_pk_mul_f32 v[74:75], v[74:75], v[238:239] op_sel_hi:[1,0]
	v_pk_mul_f32 v[76:77], v[76:77], v[238:239] op_sel_hi:[1,0]
	v_pk_mul_f32 v[78:79], v[78:79], v[238:239] op_sel_hi:[1,0]
	v_pk_mul_f32 v[80:81], v[80:81], v[238:239] op_sel_hi:[1,0]
	v_pk_mul_f32 v[82:83], v[82:83], v[238:239] op_sel_hi:[1,0]
	v_pk_mul_f32 v[52:53], v[52:53], v[238:239] op_sel_hi:[1,0]
	v_pk_mul_f32 v[54:55], v[54:55], v[238:239] op_sel_hi:[1,0]
	v_pk_mul_f32 v[56:57], v[56:57], v[238:239] op_sel_hi:[1,0]
	v_pk_mul_f32 v[58:59], v[58:59], v[238:239] op_sel_hi:[1,0]
	v_pk_mul_f32 v[60:61], v[60:61], v[238:239] op_sel_hi:[1,0]
	v_pk_mul_f32 v[62:63], v[62:63], v[238:239] op_sel_hi:[1,0]
	v_pk_mul_f32 v[64:65], v[64:65], v[238:239] op_sel_hi:[1,0]
	v_pk_mul_f32 v[66:67], v[66:67], v[238:239] op_sel_hi:[1,0]
	v_pk_mul_f32 v[36:37], v[36:37], v[238:239] op_sel_hi:[1,0]
	v_pk_mul_f32 v[38:39], v[38:39], v[238:239] op_sel_hi:[1,0]
	v_pk_mul_f32 v[40:41], v[40:41], v[238:239] op_sel_hi:[1,0]
	v_pk_mul_f32 v[42:43], v[42:43], v[238:239] op_sel_hi:[1,0]
	v_pk_mul_f32 v[44:45], v[44:45], v[238:239] op_sel_hi:[1,0]
	v_pk_mul_f32 v[46:47], v[46:47], v[238:239] op_sel_hi:[1,0]
	v_pk_mul_f32 v[48:49], v[48:49], v[238:239] op_sel_hi:[1,0]
	v_pk_mul_f32 v[50:51], v[50:51], v[238:239] op_sel_hi:[1,0]
	v_pk_mul_f32 v[20:21], v[20:21], v[238:239] op_sel_hi:[1,0]
	v_pk_mul_f32 v[22:23], v[22:23], v[238:239] op_sel_hi:[1,0]
	v_pk_mul_f32 v[24:25], v[24:25], v[238:239] op_sel_hi:[1,0]
	v_pk_mul_f32 v[26:27], v[26:27], v[238:239] op_sel_hi:[1,0]
	v_pk_mul_f32 v[28:29], v[28:29], v[238:239] op_sel_hi:[1,0]
	v_pk_mul_f32 v[30:31], v[30:31], v[238:239] op_sel_hi:[1,0]
	v_pk_mul_f32 v[32:33], v[32:33], v[238:239] op_sel_hi:[1,0]
	v_pk_mul_f32 v[34:35], v[34:35], v[238:239] op_sel_hi:[1,0]
	v_add_f32_e32 v192, v192, v236
	v_exp_f32_e32 v100, v100
	v_exp_f32_e32 v101, v101
	v_exp_f32_e32 v102, v102
	v_exp_f32_e32 v103, v103
	v_exp_f32_e32 v104, v104
	v_exp_f32_e32 v105, v105
	v_exp_f32_e32 v106, v106
	v_exp_f32_e32 v107, v107
	v_exp_f32_e32 v108, v108
	v_exp_f32_e32 v109, v109
	v_exp_f32_e32 v110, v110
	v_exp_f32_e32 v111, v111
	v_exp_f32_e32 v112, v112
	v_exp_f32_e32 v113, v113
	v_exp_f32_e32 v114, v114
	v_exp_f32_e32 v115, v115
	v_exp_f32_e32 v84, v84
	v_exp_f32_e32 v85, v85
	v_exp_f32_e32 v86, v86
	v_exp_f32_e32 v87, v87
	v_exp_f32_e32 v88, v88
	v_exp_f32_e32 v89, v89
	v_exp_f32_e32 v90, v90
	v_exp_f32_e32 v91, v91
	v_exp_f32_e32 v92, v92
	v_exp_f32_e32 v93, v93
	v_exp_f32_e32 v94, v94
	v_exp_f32_e32 v95, v95
	v_exp_f32_e32 v96, v96
	v_exp_f32_e32 v97, v97
	v_exp_f32_e32 v98, v98
	v_exp_f32_e32 v99, v99
	v_add_f32_e32 v234, 0, v100
	v_add_f32_e32 v234, v101, v234
	v_add_f32_e32 v234, v102, v234
	v_add_f32_e32 v234, v103, v234
	v_add_f32_e32 v234, v104, v234
	v_add_f32_e32 v234, v105, v234
	v_add_f32_e32 v234, v106, v234
	v_add_f32_e32 v234, v107, v234
	v_add_f32_e32 v234, v108, v234
	v_add_f32_e32 v234, v109, v234
	v_add_f32_e32 v234, v110, v234
	v_add_f32_e32 v234, v111, v234
	v_add_f32_e32 v234, v112, v234
	v_add_f32_e32 v234, v113, v234
	v_add_f32_e32 v234, v114, v234
	v_add_f32_e32 v234, v115, v234
	v_add_f32_e32 v234, v84, v234
	v_add_f32_e32 v234, v85, v234
	v_add_f32_e32 v234, v86, v234
	v_add_f32_e32 v234, v87, v234
	v_add_f32_e32 v234, v88, v234
	v_add_f32_e32 v234, v89, v234
	v_add_f32_e32 v234, v90, v234
	v_add_f32_e32 v234, v91, v234
	v_add_f32_e32 v234, v92, v234
	v_add_f32_e32 v234, v93, v234
	v_add_f32_e32 v234, v94, v234
	v_add_f32_e32 v234, v95, v234
	v_add_f32_e32 v234, v96, v234
	v_add_f32_e32 v234, v97, v234
	v_add_f32_e32 v234, v98, v234
	v_add_f32_e32 v234, v99, v234
	v_add_f32_e32 v193, v193, v234
	v_cvt_pk_bf16_f32 v226, v100, v101
	v_cvt_pk_bf16_f32 v227, v102, v103
	v_cvt_pk_bf16_f32 v228, v104, v105
	v_cvt_pk_bf16_f32 v229, v106, v107
	v_cvt_pk_bf16_f32 v230, v108, v109
	v_cvt_pk_bf16_f32 v231, v110, v111
	v_cvt_pk_bf16_f32 v232, v112, v113
	v_cvt_pk_bf16_f32 v233, v114, v115
	ds_read_b64_tr_b16 v[10:11], v197 offset:25600
	ds_read_b64_tr_b16 v[12:13], v197 offset:28160
	ds_read_b64_tr_b16 v[14:15], v197 offset:25664
	ds_read_b64_tr_b16 v[16:17], v197 offset:28224
	ds_read_b64_tr_b16 v[202:203], v197 offset:25728
	ds_read_b64_tr_b16 v[204:205], v197 offset:28288
	ds_read_b64_tr_b16 v[206:207], v197 offset:25792
	ds_read_b64_tr_b16 v[208:209], v197 offset:28352
	ds_read_b64_tr_b16 v[100:101], v197 offset:30720
	ds_read_b64_tr_b16 v[102:103], v197 offset:33280
	ds_read_b64_tr_b16 v[104:105], v197 offset:30784
	ds_read_b64_tr_b16 v[106:107], v197 offset:33344
	ds_read_b64_tr_b16 v[108:109], v197 offset:30848
	ds_read_b64_tr_b16 v[110:111], v197 offset:33408
	ds_read_b64_tr_b16 v[112:113], v197 offset:30912
	ds_read_b64_tr_b16 v[114:115], v197 offset:33472
	s_waitcnt lgkmcnt(14)
	v_mfma_f32_32x32x16_bf16 v[68:83], v[10:13], v[226:229], v[68:83]
	s_waitcnt lgkmcnt(12)
	v_mfma_f32_32x32x16_bf16 v[52:67], v[14:17], v[226:229], v[52:67]
	s_waitcnt lgkmcnt(10)
	v_mfma_f32_32x32x16_bf16 v[36:51], v[202:205], v[226:229], v[36:51]
	s_waitcnt lgkmcnt(8)
	v_mfma_f32_32x32x16_bf16 v[20:35], v[206:209], v[226:229], v[20:35]
	s_waitcnt lgkmcnt(6)
	v_mfma_f32_32x32x16_bf16 v[68:83], v[100:103], v[230:233], v[68:83]
	s_waitcnt lgkmcnt(4)
	v_mfma_f32_32x32x16_bf16 v[52:67], v[104:107], v[230:233], v[52:67]
	s_waitcnt lgkmcnt(2)
	v_mfma_f32_32x32x16_bf16 v[36:51], v[108:111], v[230:233], v[36:51]
	s_waitcnt lgkmcnt(0)
	v_mfma_f32_32x32x16_bf16 v[20:35], v[112:115], v[230:233], v[20:35]
	ds_read_b64_tr_b16 v[10:11], v197 offset:35840
	ds_read_b64_tr_b16 v[12:13], v197 offset:38400
	ds_read_b64_tr_b16 v[14:15], v197 offset:35904
	ds_read_b64_tr_b16 v[16:17], v197 offset:38464
	ds_read_b64_tr_b16 v[202:203], v197 offset:35968
	ds_read_b64_tr_b16 v[204:205], v197 offset:38528
	ds_read_b64_tr_b16 v[206:207], v197 offset:36032
	ds_read_b64_tr_b16 v[208:209], v197 offset:38592
	ds_read_b64_tr_b16 v[100:101], v197 offset:40960
	ds_read_b64_tr_b16 v[102:103], v197 offset:43520
	ds_read_b64_tr_b16 v[104:105], v197 offset:41024
	ds_read_b64_tr_b16 v[106:107], v197 offset:43584
	ds_read_b64_tr_b16 v[108:109], v197 offset:41088
	ds_read_b64_tr_b16 v[110:111], v197 offset:43648
	ds_read_b64_tr_b16 v[112:113], v197 offset:41152
	ds_read_b64_tr_b16 v[114:115], v197 offset:43712
	v_cvt_pk_bf16_f32 v226, v84, v85
	v_cvt_pk_bf16_f32 v227, v86, v87
	v_cvt_pk_bf16_f32 v228, v88, v89
	v_cvt_pk_bf16_f32 v229, v90, v91
	v_cvt_pk_bf16_f32 v230, v92, v93
	v_cvt_pk_bf16_f32 v231, v94, v95
	v_cvt_pk_bf16_f32 v232, v96, v97
	v_cvt_pk_bf16_f32 v233, v98, v99
	s_waitcnt lgkmcnt(14)
	v_mfma_f32_32x32x16_bf16 v[68:83], v[10:13], v[226:229], v[68:83]
	s_waitcnt lgkmcnt(12)
	v_mfma_f32_32x32x16_bf16 v[52:67], v[14:17], v[226:229], v[52:67]
	s_waitcnt lgkmcnt(10)
	v_mfma_f32_32x32x16_bf16 v[36:51], v[202:205], v[226:229], v[36:51]
	s_waitcnt lgkmcnt(8)
	v_mfma_f32_32x32x16_bf16 v[20:35], v[206:209], v[226:229], v[20:35]
	s_waitcnt lgkmcnt(6)
	v_mfma_f32_32x32x16_bf16 v[68:83], v[100:103], v[230:233], v[68:83]
	s_waitcnt lgkmcnt(4)
	v_mfma_f32_32x32x16_bf16 v[52:67], v[104:107], v[230:233], v[52:67]
	s_waitcnt lgkmcnt(2)
	v_mfma_f32_32x32x16_bf16 v[36:51], v[108:111], v[230:233], v[36:51]
	s_waitcnt lgkmcnt(0)
	v_mfma_f32_32x32x16_bf16 v[20:35], v[112:115], v[230:233], v[20:35]
	s_branch .LBB0_379
.Lm_RB:
	s_waitcnt lgkmcnt(0)
	ds_read_b128 v[10:13], v8 offset:12800
	ds_read_b128 v[14:17], v8 offset:12832
	ds_read_b128 v[202:205], v8 offset:12864
	ds_read_b128 v[206:209], v8 offset:12896
	s_waitcnt lgkmcnt(3)
	v_mfma_f32_32x32x16_bf16 v[84:99], v[10:13], v[116:119], v[210:225]
	ds_read_b128 v[10:13], v8 offset:12928
	s_waitcnt lgkmcnt(3)
	v_mfma_f32_32x32x16_bf16 v[84:99], v[14:17], v[120:123], v[84:99]
	ds_read_b128 v[14:17], v8 offset:12960
	s_waitcnt lgkmcnt(3)
	v_mfma_f32_32x32x16_bf16 v[84:99], v[202:205], v[124:127], v[84:99]
	ds_read_b128 v[202:205], v8 offset:12992
	s_waitcnt lgkmcnt(3)
	v_mfma_f32_32x32x16_bf16 v[84:99], v[206:209], v[132:135], v[84:99]
	ds_read_b128 v[206:209], v8 offset:13024
	s_waitcnt lgkmcnt(3)
	v_mfma_f32_32x32x16_bf16 v[84:99], v[10:13], v[136:139], v[84:99]
	ds_read_b128 v[10:13], v8 offset:13056
	s_waitcnt lgkmcnt(3)
	v_mfma_f32_32x32x16_bf16 v[84:99], v[14:17], v[140:143], v[84:99]
	ds_read_b128 v[14:17], v8 offset:13088
	s_waitcnt lgkmcnt(3)
	v_mfma_f32_32x32x16_bf16 v[84:99], v[202:205], v[144:147], v[84:99]
	ds_read_b128 v[202:205], v8 offset:13120
	s_waitcnt lgkmcnt(3)
	v_mfma_f32_32x32x16_bf16 v[84:99], v[206:209], v[148:151], v[84:99]
	ds_read_b128 v[206:209], v8 offset:13152
	s_waitcnt lgkmcnt(3)
	v_mfma_f32_32x32x16_bf16 v[84:99], v[10:13], v[152:155], v[84:99]
	s_waitcnt lgkmcnt(2)
	v_mfma_f32_32x32x16_bf16 v[84:99], v[14:17], v[156:159], v[84:99]
	s_waitcnt lgkmcnt(1)
	v_mfma_f32_32x32x16_bf16 v[84:99], v[202:205], v[160:163], v[84:99]
	s_waitcnt lgkmcnt(0)
	v_mfma_f32_32x32x16_bf16 v[84:99], v[206:209], v[164:167], v[84:99]
	s_nop 11
	v_max3_f32 v235, v84, v85, v86
	v_max3_f32 v235, v235, v87, v88
	v_max3_f32 v235, v235, v89, v90
	v_max3_f32 v235, v235, v91, v92
	v_max3_f32 v235, v235, v93, v94
	v_max3_f32 v235, v235, v95, v96
	v_max3_f32 v235, v235, v97, v98
	v_max3_f32 v235, v235, v99, v99
	v_mov_b32_e32 v237, v235
	v_mov_b32_e32 v239, v235
	s_nop 1
	v_permlane32_swap_b32_e32 v237, v239
	v_cndmask_b32_e64 v237, v237, v239, s[4:5]
	v_max_f32_e32 v237, v237, v237
	v_max_f32_e32 v236, v235, v237
	v_max_f32_e32 v236, 0, v236
	v_exp_f32_e64 v238, -v236
	v_pk_add_f32 v[84:85], v[84:85], v[236:237] op_sel_hi:[1,0] neg_lo:[0,1] neg_hi:[0,1]
	v_pk_add_f32 v[86:87], v[86:87], v[236:237] op_sel_hi:[1,0] neg_lo:[0,1] neg_hi:[0,1]
	v_pk_add_f32 v[88:89], v[88:89], v[236:237] op_sel_hi:[1,0] neg_lo:[0,1] neg_hi:[0,1]
	v_pk_add_f32 v[90:91], v[90:91], v[236:237] op_sel_hi:[1,0] neg_lo:[0,1] neg_hi:[0,1]
	v_pk_add_f32 v[92:93], v[92:93], v[236:237] op_sel_hi:[1,0] neg_lo:[0,1] neg_hi:[0,1]
	v_pk_add_f32 v[94:95], v[94:95], v[236:237] op_sel_hi:[1,0] neg_lo:[0,1] neg_hi:[0,1]
	v_pk_add_f32 v[96:97], v[96:97], v[236:237] op_sel_hi:[1,0] neg_lo:[0,1] neg_hi:[0,1]
	v_pk_add_f32 v[98:99], v[98:99], v[236:237] op_sel_hi:[1,0] neg_lo:[0,1] neg_hi:[0,1]
	v_pk_add_f32 v[210:211], v[210:211], v[236:237] op_sel_hi:[1,0] neg_lo:[0,1] neg_hi:[0,1]
	v_pk_add_f32 v[212:213], v[212:213], v[236:237] op_sel_hi:[1,0] neg_lo:[0,1] neg_hi:[0,1]
	v_pk_add_f32 v[214:215], v[214:215], v[236:237] op_sel_hi:[1,0] neg_lo:[0,1] neg_hi:[0,1]
	v_pk_add_f32 v[216:217], v[216:217], v[236:237] op_sel_hi:[1,0] neg_lo:[0,1] neg_hi:[0,1]
	v_pk_add_f32 v[218:219], v[218:219], v[236:237] op_sel_hi:[1,0] neg_lo:[0,1] neg_hi:[0,1]
	v_pk_add_f32 v[220:221], v[220:221], v[236:237] op_sel_hi:[1,0] neg_lo:[0,1] neg_hi:[0,1]
	v_pk_add_f32 v[222:223], v[222:223], v[236:237] op_sel_hi:[1,0] neg_lo:[0,1] neg_hi:[0,1]
	v_pk_add_f32 v[224:225], v[224:225], v[236:237] op_sel_hi:[1,0] neg_lo:[0,1] neg_hi:[0,1]
	v_mul_f32_e32 v193, v193, v238
	v_pk_mul_f32 v[68:69], v[68:69], v[238:239] op_sel_hi:[1,0]
	v_pk_mul_f32 v[70:71], v[70:71], v[238:239] op_sel_hi:[1,0]
	v_pk_mul_f32 v[72:73], v[72:73], v[238:239] op_sel_hi:[1,0]
	v_pk_mul_f32 v[74:75], v[74:75], v[238:239] op_sel_hi:[1,0]
	v_pk_mul_f32 v[76:77], v[76:77], v[238:239] op_sel_hi:[1,0]
	v_pk_mul_f32 v[78:79], v[78:79], v[238:239] op_sel_hi:[1,0]
	v_pk_mul_f32 v[80:81], v[80:81], v[238:239] op_sel_hi:[1,0]
	v_pk_mul_f32 v[82:83], v[82:83], v[238:239] op_sel_hi:[1,0]
	v_pk_mul_f32 v[52:53], v[52:53], v[238:239] op_sel_hi:[1,0]
	v_pk_mul_f32 v[54:55], v[54:55], v[238:239] op_sel_hi:[1,0]
	v_pk_mul_f32 v[56:57], v[56:57], v[238:239] op_sel_hi:[1,0]
	v_pk_mul_f32 v[58:59], v[58:59], v[238:239] op_sel_hi:[1,0]
	v_pk_mul_f32 v[60:61], v[60:61], v[238:239] op_sel_hi:[1,0]
	v_pk_mul_f32 v[62:63], v[62:63], v[238:239] op_sel_hi:[1,0]
	v_pk_mul_f32 v[64:65], v[64:65], v[238:239] op_sel_hi:[1,0]
	v_pk_mul_f32 v[66:67], v[66:67], v[238:239] op_sel_hi:[1,0]
	v_pk_mul_f32 v[36:37], v[36:37], v[238:239] op_sel_hi:[1,0]
	v_pk_mul_f32 v[38:39], v[38:39], v[238:239] op_sel_hi:[1,0]
	v_pk_mul_f32 v[40:41], v[40:41], v[238:239] op_sel_hi:[1,0]
	v_pk_mul_f32 v[42:43], v[42:43], v[238:239] op_sel_hi:[1,0]
	v_pk_mul_f32 v[44:45], v[44:45], v[238:239] op_sel_hi:[1,0]
	v_pk_mul_f32 v[46:47], v[46:47], v[238:239] op_sel_hi:[1,0]
	v_pk_mul_f32 v[48:49], v[48:49], v[238:239] op_sel_hi:[1,0]
	v_pk_mul_f32 v[50:51], v[50:51], v[238:239] op_sel_hi:[1,0]
	v_pk_mul_f32 v[20:21], v[20:21], v[238:239] op_sel_hi:[1,0]
	v_pk_mul_f32 v[22:23], v[22:23], v[238:239] op_sel_hi:[1,0]
	v_pk_mul_f32 v[24:25], v[24:25], v[238:239] op_sel_hi:[1,0]
	v_pk_mul_f32 v[26:27], v[26:27], v[238:239] op_sel_hi:[1,0]
	v_pk_mul_f32 v[28:29], v[28:29], v[238:239] op_sel_hi:[1,0]
	v_pk_mul_f32 v[30:31], v[30:31], v[238:239] op_sel_hi:[1,0]
	v_pk_mul_f32 v[32:33], v[32:33], v[238:239] op_sel_hi:[1,0]
	v_pk_mul_f32 v[34:35], v[34:35], v[238:239] op_sel_hi:[1,0]
	v_add_f32_e32 v192, v192, v236
	v_exp_f32_e32 v84, v84
	v_exp_f32_e32 v85, v85
	v_exp_f32_e32 v86, v86
	v_exp_f32_e32 v87, v87
	v_exp_f32_e32 v88, v88
	v_exp_f32_e32 v89, v89
	v_exp_f32_e32 v90, v90
	v_exp_f32_e32 v91, v91
	v_exp_f32_e32 v92, v92
	v_exp_f32_e32 v93, v93
	v_exp_f32_e32 v94, v94
	v_exp_f32_e32 v95, v95
	v_exp_f32_e32 v96, v96
	v_exp_f32_e32 v97, v97
	v_exp_f32_e32 v98, v98
	v_exp_f32_e32 v99, v99
	v_add_f32_e32 v240, 0, v84
	v_add_f32_e32 v240, v85, v240
	v_add_f32_e32 v240, v86, v240
	v_add_f32_e32 v240, v87, v240
	v_add_f32_e32 v240, v88, v240
	v_add_f32_e32 v240, v89, v240
	v_add_f32_e32 v240, v90, v240
	v_add_f32_e32 v240, v91, v240
	v_add_f32_e32 v240, v92, v240
	v_add_f32_e32 v240, v93, v240
	v_add_f32_e32 v240, v94, v240
	v_add_f32_e32 v240, v95, v240
	v_add_f32_e32 v240, v96, v240
	v_add_f32_e32 v240, v97, v240
	v_add_f32_e32 v240, v98, v240
	v_add_f32_e32 v240, v99, v240
	ds_read_b64_tr_b16 v[10:11], v197 offset:35840
	ds_read_b64_tr_b16 v[12:13], v197 offset:38400
	ds_read_b64_tr_b16 v[14:15], v197 offset:35904
	ds_read_b64_tr_b16 v[16:17], v197 offset:38464
	ds_read_b64_tr_b16 v[202:203], v197 offset:35968
	ds_read_b64_tr_b16 v[204:205], v197 offset:38528
	ds_read_b64_tr_b16 v[206:207], v197 offset:36032
	ds_read_b64_tr_b16 v[208:209], v197 offset:38592
	s_waitcnt lgkmcnt(0)
	s_branch .Lm_postB
